# MLA epilogue gate-load hoist added on top of GQA hoist
# baseline (speedup 1.0000x reference)
.LBB0_130:
	s_lshl_b64 s[8:9], s[8:9], 12
	s_add_u32 s8, s98, s8
	s_addc_u32 s9, s99, s9
	s_lshl_b32 s10, s20, 8
	s_add_u32 s8, s8, s10
	s_addc_u32 s9, s9, 0
	v_add_f32_e32 v82, v82, v83
	s_add_u32 s8, s8, 0x4600680
	v_fmac_f32_e32 v82, v191, v98
	s_addc_u32 s9, s9, 0
	v_add3_u32 v189, v180, v182, v190
	s_add_u32 s28, s8, 0x10000
	s_addc_u32 s29, s9, 0
	global_load_ushort v100, v189, s[28:29] offset:128
	global_load_ushort v101, v189, s[28:29] offset:192
	s_add_u32 s28, s28, 0x1000
	s_addc_u32 s29, s29, 0
	global_load_ushort v102, v189, s[28:29] offset:0
	global_load_ushort v103, v189, s[28:29] offset:64
	global_load_ushort v104, v189, s[28:29] offset:128
	global_load_ushort v105, v189, s[28:29] offset:192
	s_add_u32 s28, s28, 0x1000
	s_addc_u32 s29, s29, 0
	global_load_ushort v106, v189, s[28:29] offset:0
	global_load_ushort v107, v189, s[28:29] offset:64
	global_load_ushort v108, v189, s[28:29] offset:128
	global_load_ushort v109, v189, s[28:29] offset:192
	s_add_u32 s28, s28, 0x1000
	s_addc_u32 s29, s29, 0
	global_load_ushort v110, v189, s[28:29] offset:0
	global_load_ushort v111, v189, s[28:29] offset:64
	global_load_ushort v112, v189, s[28:29] offset:128
	global_load_ushort v113, v189, s[28:29] offset:192
	s_add_u32 s28, s28, 0x5000
	s_addc_u32 s29, s29, 0
	global_load_ushort v114, v189, s[28:29] offset:0
	global_load_ushort v115, v189, s[28:29] offset:64
	global_load_ushort v116, v189, s[28:29] offset:128
	global_load_ushort v117, v189, s[28:29] offset:192
	s_add_u32 s28, s28, 0x1000
	s_addc_u32 s29, s29, 0
	global_load_ushort v118, v189, s[28:29] offset:0
	global_load_ushort v119, v189, s[28:29] offset:64
	global_load_ushort v120, v189, s[28:29] offset:128
	global_load_ushort v121, v189, s[28:29] offset:192
	s_add_u32 s28, s28, 0x1000
	s_addc_u32 s29, s29, 0
	global_load_ushort v122, v189, s[28:29] offset:0
	global_load_ushort v123, v189, s[28:29] offset:64
	global_load_ushort v124, v189, s[28:29] offset:128
	global_load_ushort v125, v189, s[28:29] offset:192
	s_add_u32 s28, s28, 0x1000
	s_addc_u32 s29, s29, 0
	global_load_ushort v126, v189, s[28:29] offset:0
	global_load_ushort v127, v189, s[28:29] offset:64
	global_load_ushort v128, v189, s[28:29] offset:128
	global_load_ushort v129, v189, s[28:29] offset:192
	s_nop 0
	s_nop 0
	s_nop 0
	s_nop 0
	s_nop 0
	s_nop 0
	s_nop 0
	s_nop 0
	s_nop 0
	s_nop 0
	s_waitcnt vmcnt(30)
	s_barrier
	v_lshl_add_u32 v83, s12, 14, v233
	ds_read_b64_tr_b16 v[84:85], v83 offset:0
	ds_read_b64_tr_b16 v[86:87], v83 offset:0x800
	ds_read_b64_tr_b16 v[88:89], v83 offset:0x1000
	ds_read_b64_tr_b16 v[90:91], v83 offset:0x1800
	ds_read_b64_tr_b16 v[92:93], v83 offset:0x2000
	ds_read_b64_tr_b16 v[94:95], v83 offset:0x2800
	ds_read_b64_tr_b16 v[96:97], v83 offset:0x3000
	ds_read_b64_tr_b16 v[98:99], v83 offset:0x3800
	s_waitcnt lgkmcnt(0)
	s_nop 0
	v_mfma_f32_32x32x16_bf16 v[2:17], v[78:81], v[84:87], v[2:17]
	ds_read_b64_tr_b16 v[84:85], v83 offset:0x200
	ds_read_b64_tr_b16 v[86:87], v83 offset:0xa00
	v_mfma_f32_32x32x16_bf16 v[2:17], v[74:77], v[88:91], v[2:17]
	ds_read_b64_tr_b16 v[88:89], v83 offset:0x1200
	ds_read_b64_tr_b16 v[90:91], v83 offset:0x1a00
	v_mfma_f32_32x32x16_bf16 v[2:17], v[70:73], v[92:95], v[2:17]
	ds_read_b64_tr_b16 v[92:93], v83 offset:0x2200
	ds_read_b64_tr_b16 v[94:95], v83 offset:0x2a00
	v_mfma_f32_32x32x16_bf16 v[2:17], v[66:69], v[96:99], v[2:17]
	ds_read_b64_tr_b16 v[96:97], v83 offset:0x3200
	ds_read_b64_tr_b16 v[98:99], v83 offset:0x3a00
	s_waitcnt lgkmcnt(0)
	v_mfma_f32_32x32x16_bf16 v[18:33], v[78:81], v[84:87], v[18:33]
	ds_read_b64_tr_b16 v[84:85], v83 offset:0x400
	ds_read_b64_tr_b16 v[86:87], v83 offset:0xc00
	v_mfma_f32_32x32x16_bf16 v[18:33], v[74:77], v[88:91], v[18:33]
	ds_read_b64_tr_b16 v[88:89], v83 offset:0x1400
	ds_read_b64_tr_b16 v[90:91], v83 offset:0x1c00
	v_mfma_f32_32x32x16_bf16 v[18:33], v[70:73], v[92:95], v[18:33]
	ds_read_b64_tr_b16 v[92:93], v83 offset:0x2400
	ds_read_b64_tr_b16 v[94:95], v83 offset:0x2c00
	v_mfma_f32_32x32x16_bf16 v[18:33], v[66:69], v[96:99], v[18:33]
	ds_read_b64_tr_b16 v[96:97], v83 offset:0x3400
	ds_read_b64_tr_b16 v[98:99], v83 offset:0x3c00
	s_waitcnt lgkmcnt(0)
	v_mfma_f32_32x32x16_bf16 v[34:49], v[78:81], v[84:87], v[34:49]
	ds_read_b64_tr_b16 v[84:85], v83 offset:0x600
	ds_read_b64_tr_b16 v[86:87], v83 offset:0xe00
	v_mfma_f32_32x32x16_bf16 v[34:49], v[74:77], v[88:91], v[34:49]
	ds_read_b64_tr_b16 v[88:89], v83 offset:0x1600
	ds_read_b64_tr_b16 v[90:91], v83 offset:0x1e00
	v_mfma_f32_32x32x16_bf16 v[34:49], v[70:73], v[92:95], v[34:49]
	ds_read_b64_tr_b16 v[92:93], v83 offset:0x2600
	ds_read_b64_tr_b16 v[94:95], v83 offset:0x2e00
	v_mfma_f32_32x32x16_bf16 v[34:49], v[66:69], v[96:99], v[34:49]
	ds_read_b64_tr_b16 v[96:97], v83 offset:0x3600
	ds_read_b64_tr_b16 v[98:99], v83 offset:0x3e00
	s_waitcnt lgkmcnt(0)
	v_mfma_f32_32x32x16_bf16 v[50:65], v[78:81], v[84:87], v[50:65]
	s_and_b64 vcc, exec, s[6:7]
	s_barrier
	v_mfma_f32_32x32x16_bf16 v[50:65], v[74:77], v[88:91], v[50:65]
	v_mfma_f32_32x32x16_bf16 v[50:65], v[70:73], v[92:95], v[50:65]
	v_mfma_f32_32x32x16_bf16 v[50:65], v[66:69], v[96:99], v[50:65]
	s_cbranch_vccz .LBB0_134
	s_and_saveexec_b64 s[10:11], s[4:5]
	ds_write_b32 v232, v82
	s_or_b64 exec, exec, s[10:11]
	s_waitcnt lgkmcnt(0)
	v_add_u32_e32 v191, v196, v202
	ds_read_b128 v[130:133], v191
	ds_read_b128 v[134:137], v191 offset:32
	ds_read_b128 v[138:141], v191 offset:64
	ds_read_b128 v[142:145], v191 offset:96
	s_mov_b32 s12, s8
	s_mov_b32 s13, s9
	global_load_ushort v66, v189, s[12:13] offset:0
	global_load_ushort v67, v189, s[12:13] offset:64
	global_load_ushort v68, v189, s[12:13] offset:128
	global_load_ushort v69, v189, s[12:13] offset:192
	s_add_u32 s12, s12, 0x1000
	s_addc_u32 s13, s13, 0
	global_load_ushort v70, v189, s[12:13] offset:0
	global_load_ushort v71, v189, s[12:13] offset:64
	global_load_ushort v72, v189, s[12:13] offset:128
	global_load_ushort v73, v189, s[12:13] offset:192
	s_add_u32 s12, s12, 0x1000
	s_addc_u32 s13, s13, 0
	global_load_ushort v74, v189, s[12:13] offset:0
	global_load_ushort v75, v189, s[12:13] offset:64
	global_load_ushort v76, v189, s[12:13] offset:128
	global_load_ushort v77, v189, s[12:13] offset:192
	s_add_u32 s12, s12, 0x1000
	s_addc_u32 s13, s13, 0
	global_load_ushort v78, v189, s[12:13] offset:0
	global_load_ushort v79, v189, s[12:13] offset:64
	global_load_ushort v80, v189, s[12:13] offset:128
	global_load_ushort v81, v189, s[12:13] offset:192
	s_add_u32 s12, s12, 0x5000
	s_addc_u32 s13, s13, 0
	global_load_ushort v82, v189, s[12:13] offset:0
	global_load_ushort v83, v189, s[12:13] offset:64
	global_load_ushort v84, v189, s[12:13] offset:128
	global_load_ushort v85, v189, s[12:13] offset:192
	s_add_u32 s12, s12, 0x1000
	s_addc_u32 s13, s13, 0
	global_load_ushort v86, v189, s[12:13] offset:0
	global_load_ushort v87, v189, s[12:13] offset:64
	global_load_ushort v88, v189, s[12:13] offset:128
	global_load_ushort v89, v189, s[12:13] offset:192
	s_add_u32 s12, s12, 0x1000
	s_addc_u32 s13, s13, 0
	global_load_ushort v90, v189, s[12:13] offset:0
	global_load_ushort v91, v189, s[12:13] offset:64
	global_load_ushort v92, v189, s[12:13] offset:128
	global_load_ushort v93, v189, s[12:13] offset:192
	s_add_u32 s12, s12, 0x1000
	s_addc_u32 s13, s13, 0
	global_load_ushort v94, v189, s[12:13] offset:0
	global_load_ushort v95, v189, s[12:13] offset:64
	global_load_ushort v96, v189, s[12:13] offset:128
	global_load_ushort v97, v189, s[12:13] offset:192
	s_add_u32 s12, s12, 0x5000
	s_addc_u32 s13, s13, 0
	global_load_ushort v98, v189, s[12:13] offset:0
	global_load_ushort v99, v189, s[12:13] offset:64
	s_nop 0
	s_nop 0
	s_nop 0
	s_waitcnt lgkmcnt(0)
	v_rcp_f32_e32 v146, v130
	v_rcp_f32_e32 v147, v131
	v_rcp_f32_e32 v148, v132
	v_rcp_f32_e32 v149, v133
	v_rcp_f32_e32 v150, v134
	v_rcp_f32_e32 v151, v135
	v_rcp_f32_e32 v152, v136
	v_rcp_f32_e32 v153, v137
	v_rcp_f32_e32 v154, v138
	v_rcp_f32_e32 v155, v139
	v_rcp_f32_e32 v156, v140
	v_rcp_f32_e32 v157, v141
	v_rcp_f32_e32 v158, v142
	v_rcp_f32_e32 v159, v143
	v_rcp_f32_e32 v160, v144
	v_rcp_f32_e32 v161, v145
	s_waitcnt vmcnt(62)
	v_lshlrev_b32_e32 v100, 16, v100
	v_lshlrev_b32_e32 v101, 16, v101
	v_mul_f32_e32 v162, 0xbfb8aa3b, v100
	v_mul_f32_e32 v163, 0xbfb8aa3b, v101
	v_exp_f32_e32 v162, v162
	v_exp_f32_e32 v163, v163
	v_mul_f32_e32 v164, v42, v154
	v_mul_f32_e32 v165, v58, v154
	v_add_f32_e32 v162, 1.0, v162
	v_add_f32_e32 v163, 1.0, v163
	v_rcp_f32_e32 v162, v162
	v_rcp_f32_e32 v163, v163
	s_nop 0
	v_mul_f32_e32 v100, v162, v100
	v_mul_f32_e32 v101, v163, v101
	v_mul_f32_e32 v100, v164, v100
	v_mul_f32_e32 v101, v165, v101
	v_cvt_pk_bf16_f32 v100, v100, v100
	v_cvt_pk_bf16_f32 v101, v101, v101
	s_waitcnt vmcnt(60)
	v_lshlrev_b32_e32 v102, 16, v102
	v_lshlrev_b32_e32 v103, 16, v103
	v_mul_f32_e32 v162, 0xbfb8aa3b, v102
	v_mul_f32_e32 v163, 0xbfb8aa3b, v103
	v_exp_f32_e32 v162, v162
	v_exp_f32_e32 v163, v163
	v_mul_f32_e32 v164, v11, v155
	v_mul_f32_e32 v165, v27, v155
	v_add_f32_e32 v162, 1.0, v162
	v_add_f32_e32 v163, 1.0, v163
	v_rcp_f32_e32 v162, v162
	v_rcp_f32_e32 v163, v163
	s_nop 0
	v_mul_f32_e32 v102, v162, v102
	v_mul_f32_e32 v103, v163, v103
	v_mul_f32_e32 v102, v164, v102
	v_mul_f32_e32 v103, v165, v103
	v_cvt_pk_bf16_f32 v102, v102, v102
	v_cvt_pk_bf16_f32 v103, v103, v103
	s_waitcnt vmcnt(58)
	v_lshlrev_b32_e32 v104, 16, v104
	v_lshlrev_b32_e32 v105, 16, v105
	v_mul_f32_e32 v162, 0xbfb8aa3b, v104
	v_mul_f32_e32 v163, 0xbfb8aa3b, v105
	v_exp_f32_e32 v162, v162
	v_exp_f32_e32 v163, v163
	v_mul_f32_e32 v164, v43, v155
	v_mul_f32_e32 v165, v59, v155
	v_add_f32_e32 v162, 1.0, v162
	v_add_f32_e32 v163, 1.0, v163
	v_rcp_f32_e32 v162, v162
	v_rcp_f32_e32 v163, v163
	s_nop 0
	v_mul_f32_e32 v104, v162, v104
	v_mul_f32_e32 v105, v163, v105
	v_mul_f32_e32 v104, v164, v104
	v_mul_f32_e32 v105, v165, v105
	v_cvt_pk_bf16_f32 v104, v104, v104
	v_cvt_pk_bf16_f32 v105, v105, v105
	s_waitcnt vmcnt(56)
	v_lshlrev_b32_e32 v106, 16, v106
	v_lshlrev_b32_e32 v107, 16, v107
	v_mul_f32_e32 v162, 0xbfb8aa3b, v106
	v_mul_f32_e32 v163, 0xbfb8aa3b, v107
	v_exp_f32_e32 v162, v162
	v_exp_f32_e32 v163, v163
	v_mul_f32_e32 v164, v12, v156
	v_mul_f32_e32 v165, v28, v156
	v_add_f32_e32 v162, 1.0, v162
	v_add_f32_e32 v163, 1.0, v163
	v_rcp_f32_e32 v162, v162
	v_rcp_f32_e32 v163, v163
	s_nop 0
	v_mul_f32_e32 v106, v162, v106
	v_mul_f32_e32 v107, v163, v107
	v_mul_f32_e32 v106, v164, v106
	v_mul_f32_e32 v107, v165, v107
	v_cvt_pk_bf16_f32 v106, v106, v106
	v_cvt_pk_bf16_f32 v107, v107, v107
	s_waitcnt vmcnt(54)
	v_lshlrev_b32_e32 v108, 16, v108
	v_lshlrev_b32_e32 v109, 16, v109
	v_mul_f32_e32 v162, 0xbfb8aa3b, v108
	v_mul_f32_e32 v163, 0xbfb8aa3b, v109
	v_exp_f32_e32 v162, v162
	v_exp_f32_e32 v163, v163
	v_mul_f32_e32 v164, v44, v156
	v_mul_f32_e32 v165, v60, v156
	v_add_f32_e32 v162, 1.0, v162
	v_add_f32_e32 v163, 1.0, v163
	v_rcp_f32_e32 v162, v162
	v_rcp_f32_e32 v163, v163
	s_nop 0
	v_mul_f32_e32 v108, v162, v108
	v_mul_f32_e32 v109, v163, v109
	v_mul_f32_e32 v108, v164, v108
	v_mul_f32_e32 v109, v165, v109
	v_cvt_pk_bf16_f32 v108, v108, v108
	v_cvt_pk_bf16_f32 v109, v109, v109
	s_waitcnt vmcnt(52)
	v_lshlrev_b32_e32 v110, 16, v110
	v_lshlrev_b32_e32 v111, 16, v111
	v_mul_f32_e32 v162, 0xbfb8aa3b, v110
	v_mul_f32_e32 v163, 0xbfb8aa3b, v111
	v_exp_f32_e32 v162, v162
	v_exp_f32_e32 v163, v163
	v_mul_f32_e32 v164, v13, v157
	v_mul_f32_e32 v165, v29, v157
	v_add_f32_e32 v162, 1.0, v162
	v_add_f32_e32 v163, 1.0, v163
	v_rcp_f32_e32 v162, v162
	v_rcp_f32_e32 v163, v163
	s_nop 0
	v_mul_f32_e32 v110, v162, v110
	v_mul_f32_e32 v111, v163, v111
	v_mul_f32_e32 v110, v164, v110
	v_mul_f32_e32 v111, v165, v111
	v_cvt_pk_bf16_f32 v110, v110, v110
	v_cvt_pk_bf16_f32 v111, v111, v111
	s_waitcnt vmcnt(50)
	v_lshlrev_b32_e32 v112, 16, v112
	v_lshlrev_b32_e32 v113, 16, v113
	v_mul_f32_e32 v162, 0xbfb8aa3b, v112
	v_mul_f32_e32 v163, 0xbfb8aa3b, v113
	v_exp_f32_e32 v162, v162
	v_exp_f32_e32 v163, v163
	v_mul_f32_e32 v164, v45, v157
	v_mul_f32_e32 v165, v61, v157
	v_add_f32_e32 v162, 1.0, v162
	v_add_f32_e32 v163, 1.0, v163
	v_rcp_f32_e32 v162, v162
	v_rcp_f32_e32 v163, v163
	s_nop 0
	v_mul_f32_e32 v112, v162, v112
	v_mul_f32_e32 v113, v163, v113
	v_mul_f32_e32 v112, v164, v112
	v_mul_f32_e32 v113, v165, v113
	v_cvt_pk_bf16_f32 v112, v112, v112
	v_cvt_pk_bf16_f32 v113, v113, v113
	s_waitcnt vmcnt(48)
	v_lshlrev_b32_e32 v114, 16, v114
	v_lshlrev_b32_e32 v115, 16, v115
	v_mul_f32_e32 v162, 0xbfb8aa3b, v114
	v_mul_f32_e32 v163, 0xbfb8aa3b, v115
	v_exp_f32_e32 v162, v162
	v_exp_f32_e32 v163, v163
	v_mul_f32_e32 v164, v14, v158
	v_mul_f32_e32 v165, v30, v158
	v_add_f32_e32 v162, 1.0, v162
	v_add_f32_e32 v163, 1.0, v163
	v_rcp_f32_e32 v162, v162
	v_rcp_f32_e32 v163, v163
	s_nop 0
	v_mul_f32_e32 v114, v162, v114
	v_mul_f32_e32 v115, v163, v115
	v_mul_f32_e32 v114, v164, v114
	v_mul_f32_e32 v115, v165, v115
	v_cvt_pk_bf16_f32 v114, v114, v114
	v_cvt_pk_bf16_f32 v115, v115, v115
	s_waitcnt vmcnt(46)
	v_lshlrev_b32_e32 v116, 16, v116
	v_lshlrev_b32_e32 v117, 16, v117
	v_mul_f32_e32 v162, 0xbfb8aa3b, v116
	v_mul_f32_e32 v163, 0xbfb8aa3b, v117
	v_exp_f32_e32 v162, v162
	v_exp_f32_e32 v163, v163
	v_mul_f32_e32 v164, v46, v158
	v_mul_f32_e32 v165, v62, v158
	v_add_f32_e32 v162, 1.0, v162
	v_add_f32_e32 v163, 1.0, v163
	v_rcp_f32_e32 v162, v162
	v_rcp_f32_e32 v163, v163
	s_nop 0
	v_mul_f32_e32 v116, v162, v116
	v_mul_f32_e32 v117, v163, v117
	v_mul_f32_e32 v116, v164, v116
	v_mul_f32_e32 v117, v165, v117
	v_cvt_pk_bf16_f32 v116, v116, v116
	v_cvt_pk_bf16_f32 v117, v117, v117
	s_waitcnt vmcnt(44)
	v_lshlrev_b32_e32 v118, 16, v118
	v_lshlrev_b32_e32 v119, 16, v119
	v_mul_f32_e32 v162, 0xbfb8aa3b, v118
	v_mul_f32_e32 v163, 0xbfb8aa3b, v119
	v_exp_f32_e32 v162, v162
	v_exp_f32_e32 v163, v163
	v_mul_f32_e32 v164, v15, v159
	v_mul_f32_e32 v165, v31, v159
	v_add_f32_e32 v162, 1.0, v162
	v_add_f32_e32 v163, 1.0, v163
	v_rcp_f32_e32 v162, v162
	v_rcp_f32_e32 v163, v163
	s_nop 0
	v_mul_f32_e32 v118, v162, v118
	v_mul_f32_e32 v119, v163, v119
	v_mul_f32_e32 v118, v164, v118
	v_mul_f32_e32 v119, v165, v119
	v_cvt_pk_bf16_f32 v118, v118, v118
	v_cvt_pk_bf16_f32 v119, v119, v119
	s_waitcnt vmcnt(42)
	v_lshlrev_b32_e32 v120, 16, v120
	v_lshlrev_b32_e32 v121, 16, v121
	v_mul_f32_e32 v162, 0xbfb8aa3b, v120
	v_mul_f32_e32 v163, 0xbfb8aa3b, v121
	v_exp_f32_e32 v162, v162
	v_exp_f32_e32 v163, v163
	v_mul_f32_e32 v164, v47, v159
	v_mul_f32_e32 v165, v63, v159
	v_add_f32_e32 v162, 1.0, v162
	v_add_f32_e32 v163, 1.0, v163
	v_rcp_f32_e32 v162, v162
	v_rcp_f32_e32 v163, v163
	s_nop 0
	v_mul_f32_e32 v120, v162, v120
	v_mul_f32_e32 v121, v163, v121
	v_mul_f32_e32 v120, v164, v120
	v_mul_f32_e32 v121, v165, v121
	v_cvt_pk_bf16_f32 v120, v120, v120
	v_cvt_pk_bf16_f32 v121, v121, v121
	s_waitcnt vmcnt(40)
	v_lshlrev_b32_e32 v122, 16, v122
	v_lshlrev_b32_e32 v123, 16, v123
	v_mul_f32_e32 v162, 0xbfb8aa3b, v122
	v_mul_f32_e32 v163, 0xbfb8aa3b, v123
	v_exp_f32_e32 v162, v162
	v_exp_f32_e32 v163, v163
	v_mul_f32_e32 v164, v16, v160
	v_mul_f32_e32 v165, v32, v160
	v_add_f32_e32 v162, 1.0, v162
	v_add_f32_e32 v163, 1.0, v163
	v_rcp_f32_e32 v162, v162
	v_rcp_f32_e32 v163, v163
	s_nop 0
	v_mul_f32_e32 v122, v162, v122
	v_mul_f32_e32 v123, v163, v123
	v_mul_f32_e32 v122, v164, v122
	v_mul_f32_e32 v123, v165, v123
	v_cvt_pk_bf16_f32 v122, v122, v122
	v_cvt_pk_bf16_f32 v123, v123, v123
	s_waitcnt vmcnt(38)
	v_lshlrev_b32_e32 v124, 16, v124
	v_lshlrev_b32_e32 v125, 16, v125
	v_mul_f32_e32 v162, 0xbfb8aa3b, v124
	v_mul_f32_e32 v163, 0xbfb8aa3b, v125
	v_exp_f32_e32 v162, v162
	v_exp_f32_e32 v163, v163
	v_mul_f32_e32 v164, v48, v160
	v_mul_f32_e32 v165, v64, v160
	v_add_f32_e32 v162, 1.0, v162
	v_add_f32_e32 v163, 1.0, v163
	v_rcp_f32_e32 v162, v162
	v_rcp_f32_e32 v163, v163
	s_nop 0
	v_mul_f32_e32 v124, v162, v124
	v_mul_f32_e32 v125, v163, v125
	v_mul_f32_e32 v124, v164, v124
	v_mul_f32_e32 v125, v165, v125
	v_cvt_pk_bf16_f32 v124, v124, v124
	v_cvt_pk_bf16_f32 v125, v125, v125
	s_waitcnt vmcnt(36)
	v_lshlrev_b32_e32 v126, 16, v126
	v_lshlrev_b32_e32 v127, 16, v127
	v_mul_f32_e32 v162, 0xbfb8aa3b, v126
	v_mul_f32_e32 v163, 0xbfb8aa3b, v127
	v_exp_f32_e32 v162, v162
	v_exp_f32_e32 v163, v163
	v_mul_f32_e32 v164, v17, v161
	v_mul_f32_e32 v165, v33, v161
	v_add_f32_e32 v162, 1.0, v162
	v_add_f32_e32 v163, 1.0, v163
	v_rcp_f32_e32 v162, v162
	v_rcp_f32_e32 v163, v163
	s_nop 0
	v_mul_f32_e32 v126, v162, v126
	v_mul_f32_e32 v127, v163, v127
	v_mul_f32_e32 v126, v164, v126
	v_mul_f32_e32 v127, v165, v127
	v_cvt_pk_bf16_f32 v126, v126, v126
	v_cvt_pk_bf16_f32 v127, v127, v127
	s_waitcnt vmcnt(34)
	v_lshlrev_b32_e32 v128, 16, v128
	v_lshlrev_b32_e32 v129, 16, v129
	v_mul_f32_e32 v162, 0xbfb8aa3b, v128
	v_mul_f32_e32 v163, 0xbfb8aa3b, v129
	v_exp_f32_e32 v162, v162
	v_exp_f32_e32 v163, v163
	v_mul_f32_e32 v164, v49, v161
	v_mul_f32_e32 v165, v65, v161
	v_add_f32_e32 v162, 1.0, v162
	v_add_f32_e32 v163, 1.0, v163
	v_rcp_f32_e32 v162, v162
	v_rcp_f32_e32 v163, v163
	s_nop 0
	v_mul_f32_e32 v128, v162, v128
	v_mul_f32_e32 v129, v163, v129
	v_mul_f32_e32 v128, v164, v128
	v_mul_f32_e32 v129, v165, v129
	v_cvt_pk_bf16_f32 v128, v128, v128
	v_cvt_pk_bf16_f32 v129, v129, v129
	s_waitcnt vmcnt(32)
	v_lshlrev_b32_e32 v66, 16, v66
	v_lshlrev_b32_e32 v67, 16, v67
	v_mul_f32_e32 v162, 0xbfb8aa3b, v66
	v_mul_f32_e32 v163, 0xbfb8aa3b, v67
	v_exp_f32_e32 v162, v162
	v_exp_f32_e32 v163, v163
	v_mul_f32_e32 v164, v2, v146
	v_mul_f32_e32 v165, v18, v146
	v_add_f32_e32 v162, 1.0, v162
	v_add_f32_e32 v163, 1.0, v163
	v_rcp_f32_e32 v162, v162
	v_rcp_f32_e32 v163, v163
	s_nop 0
	v_mul_f32_e32 v66, v162, v66
	v_mul_f32_e32 v67, v163, v67
	v_mul_f32_e32 v66, v164, v66
	v_mul_f32_e32 v67, v165, v67
	v_cvt_pk_bf16_f32 v66, v66, v66
	v_cvt_pk_bf16_f32 v67, v67, v67
	s_waitcnt vmcnt(30)
	v_lshlrev_b32_e32 v68, 16, v68
	v_lshlrev_b32_e32 v69, 16, v69
	v_mul_f32_e32 v162, 0xbfb8aa3b, v68
	v_mul_f32_e32 v163, 0xbfb8aa3b, v69
	v_exp_f32_e32 v162, v162
	v_exp_f32_e32 v163, v163
	v_mul_f32_e32 v164, v34, v146
	v_mul_f32_e32 v165, v50, v146
	v_add_f32_e32 v162, 1.0, v162
	v_add_f32_e32 v163, 1.0, v163
	v_rcp_f32_e32 v162, v162
	v_rcp_f32_e32 v163, v163
	s_nop 0
	v_mul_f32_e32 v68, v162, v68
	v_mul_f32_e32 v69, v163, v69
	v_mul_f32_e32 v68, v164, v68
	v_mul_f32_e32 v69, v165, v69
	v_cvt_pk_bf16_f32 v68, v68, v68
	v_cvt_pk_bf16_f32 v69, v69, v69
	s_waitcnt vmcnt(28)
	v_lshlrev_b32_e32 v70, 16, v70
	v_lshlrev_b32_e32 v71, 16, v71
	v_mul_f32_e32 v162, 0xbfb8aa3b, v70
	v_mul_f32_e32 v163, 0xbfb8aa3b, v71
	v_exp_f32_e32 v162, v162
	v_exp_f32_e32 v163, v163
	v_mul_f32_e32 v164, v3, v147
	v_mul_f32_e32 v165, v19, v147
	v_add_f32_e32 v162, 1.0, v162
	v_add_f32_e32 v163, 1.0, v163
	v_rcp_f32_e32 v162, v162
	v_rcp_f32_e32 v163, v163
	s_nop 0
	v_mul_f32_e32 v70, v162, v70
	v_mul_f32_e32 v71, v163, v71
	v_mul_f32_e32 v70, v164, v70
	v_mul_f32_e32 v71, v165, v71
	v_cvt_pk_bf16_f32 v70, v70, v70
	v_cvt_pk_bf16_f32 v71, v71, v71
	s_waitcnt vmcnt(26)
	v_lshlrev_b32_e32 v72, 16, v72
	v_lshlrev_b32_e32 v73, 16, v73
	v_mul_f32_e32 v162, 0xbfb8aa3b, v72
	v_mul_f32_e32 v163, 0xbfb8aa3b, v73
	v_exp_f32_e32 v162, v162
	v_exp_f32_e32 v163, v163
	v_mul_f32_e32 v164, v35, v147
	v_mul_f32_e32 v165, v51, v147
	v_add_f32_e32 v162, 1.0, v162
	v_add_f32_e32 v163, 1.0, v163
	v_rcp_f32_e32 v162, v162
	v_rcp_f32_e32 v163, v163
	s_nop 0
	v_mul_f32_e32 v72, v162, v72
	v_mul_f32_e32 v73, v163, v73
	v_mul_f32_e32 v72, v164, v72
	v_mul_f32_e32 v73, v165, v73
	v_cvt_pk_bf16_f32 v72, v72, v72
	v_cvt_pk_bf16_f32 v73, v73, v73
	s_waitcnt vmcnt(24)
	v_lshlrev_b32_e32 v74, 16, v74
	v_lshlrev_b32_e32 v75, 16, v75
	v_mul_f32_e32 v162, 0xbfb8aa3b, v74
	v_mul_f32_e32 v163, 0xbfb8aa3b, v75
	v_exp_f32_e32 v162, v162
	v_exp_f32_e32 v163, v163
	v_mul_f32_e32 v164, v4, v148
	v_mul_f32_e32 v165, v20, v148
	v_add_f32_e32 v162, 1.0, v162
	v_add_f32_e32 v163, 1.0, v163
	v_rcp_f32_e32 v162, v162
	v_rcp_f32_e32 v163, v163
	s_nop 0
	v_mul_f32_e32 v74, v162, v74
	v_mul_f32_e32 v75, v163, v75
	v_mul_f32_e32 v74, v164, v74
	v_mul_f32_e32 v75, v165, v75
	v_cvt_pk_bf16_f32 v74, v74, v74
	v_cvt_pk_bf16_f32 v75, v75, v75
	s_waitcnt vmcnt(22)
	v_lshlrev_b32_e32 v76, 16, v76
	v_lshlrev_b32_e32 v77, 16, v77
	v_mul_f32_e32 v162, 0xbfb8aa3b, v76
	v_mul_f32_e32 v163, 0xbfb8aa3b, v77
	v_exp_f32_e32 v162, v162
	v_exp_f32_e32 v163, v163
	v_mul_f32_e32 v164, v36, v148
	v_mul_f32_e32 v165, v52, v148
	v_add_f32_e32 v162, 1.0, v162
	v_add_f32_e32 v163, 1.0, v163
	v_rcp_f32_e32 v162, v162
	v_rcp_f32_e32 v163, v163
	s_nop 0
	v_mul_f32_e32 v76, v162, v76
	v_mul_f32_e32 v77, v163, v77
	v_mul_f32_e32 v76, v164, v76
	v_mul_f32_e32 v77, v165, v77
	v_cvt_pk_bf16_f32 v76, v76, v76
	v_cvt_pk_bf16_f32 v77, v77, v77
	s_waitcnt vmcnt(20)
	v_lshlrev_b32_e32 v78, 16, v78
	v_lshlrev_b32_e32 v79, 16, v79
	v_mul_f32_e32 v162, 0xbfb8aa3b, v78
	v_mul_f32_e32 v163, 0xbfb8aa3b, v79
	v_exp_f32_e32 v162, v162
	v_exp_f32_e32 v163, v163
	v_mul_f32_e32 v164, v5, v149
	v_mul_f32_e32 v165, v21, v149
	v_add_f32_e32 v162, 1.0, v162
	v_add_f32_e32 v163, 1.0, v163
	v_rcp_f32_e32 v162, v162
	v_rcp_f32_e32 v163, v163
	s_nop 0
	v_mul_f32_e32 v78, v162, v78
	v_mul_f32_e32 v79, v163, v79
	v_mul_f32_e32 v78, v164, v78
	v_mul_f32_e32 v79, v165, v79
	v_cvt_pk_bf16_f32 v78, v78, v78
	v_cvt_pk_bf16_f32 v79, v79, v79
	s_waitcnt vmcnt(18)
	v_lshlrev_b32_e32 v80, 16, v80
	v_lshlrev_b32_e32 v81, 16, v81
	v_mul_f32_e32 v162, 0xbfb8aa3b, v80
	v_mul_f32_e32 v163, 0xbfb8aa3b, v81
	v_exp_f32_e32 v162, v162
	v_exp_f32_e32 v163, v163
	v_mul_f32_e32 v164, v37, v149
	v_mul_f32_e32 v165, v53, v149
	v_add_f32_e32 v162, 1.0, v162
	v_add_f32_e32 v163, 1.0, v163
	v_rcp_f32_e32 v162, v162
	v_rcp_f32_e32 v163, v163
	s_nop 0
	v_mul_f32_e32 v80, v162, v80
	v_mul_f32_e32 v81, v163, v81
	v_mul_f32_e32 v80, v164, v80
	v_mul_f32_e32 v81, v165, v81
	v_cvt_pk_bf16_f32 v80, v80, v80
	v_cvt_pk_bf16_f32 v81, v81, v81
	s_waitcnt vmcnt(16)
	v_lshlrev_b32_e32 v82, 16, v82
	v_lshlrev_b32_e32 v83, 16, v83
	v_mul_f32_e32 v162, 0xbfb8aa3b, v82
	v_mul_f32_e32 v163, 0xbfb8aa3b, v83
	v_exp_f32_e32 v162, v162
	v_exp_f32_e32 v163, v163
	v_mul_f32_e32 v164, v6, v150
	v_mul_f32_e32 v165, v22, v150
	v_add_f32_e32 v162, 1.0, v162
	v_add_f32_e32 v163, 1.0, v163
	v_rcp_f32_e32 v162, v162
	v_rcp_f32_e32 v163, v163
	s_nop 0
	v_mul_f32_e32 v82, v162, v82
	v_mul_f32_e32 v83, v163, v83
	v_mul_f32_e32 v82, v164, v82
	v_mul_f32_e32 v83, v165, v83
	v_cvt_pk_bf16_f32 v82, v82, v82
	v_cvt_pk_bf16_f32 v83, v83, v83
	s_waitcnt vmcnt(14)
	v_lshlrev_b32_e32 v84, 16, v84
	v_lshlrev_b32_e32 v85, 16, v85
	v_mul_f32_e32 v162, 0xbfb8aa3b, v84
	v_mul_f32_e32 v163, 0xbfb8aa3b, v85
	v_exp_f32_e32 v162, v162
	v_exp_f32_e32 v163, v163
	v_mul_f32_e32 v164, v38, v150
	v_mul_f32_e32 v165, v54, v150
	v_add_f32_e32 v162, 1.0, v162
	v_add_f32_e32 v163, 1.0, v163
	v_rcp_f32_e32 v162, v162
	v_rcp_f32_e32 v163, v163
	s_nop 0
	v_mul_f32_e32 v84, v162, v84
	v_mul_f32_e32 v85, v163, v85
	v_mul_f32_e32 v84, v164, v84
	v_mul_f32_e32 v85, v165, v85
	v_cvt_pk_bf16_f32 v84, v84, v84
	v_cvt_pk_bf16_f32 v85, v85, v85
	s_waitcnt vmcnt(12)
	v_lshlrev_b32_e32 v86, 16, v86
	v_lshlrev_b32_e32 v87, 16, v87
	v_mul_f32_e32 v162, 0xbfb8aa3b, v86
	v_mul_f32_e32 v163, 0xbfb8aa3b, v87
	v_exp_f32_e32 v162, v162
	v_exp_f32_e32 v163, v163
	v_mul_f32_e32 v164, v7, v151
	v_mul_f32_e32 v165, v23, v151
	v_add_f32_e32 v162, 1.0, v162
	v_add_f32_e32 v163, 1.0, v163
	v_rcp_f32_e32 v162, v162
	v_rcp_f32_e32 v163, v163
	s_nop 0
	v_mul_f32_e32 v86, v162, v86
	v_mul_f32_e32 v87, v163, v87
	v_mul_f32_e32 v86, v164, v86
	v_mul_f32_e32 v87, v165, v87
	v_cvt_pk_bf16_f32 v86, v86, v86
	v_cvt_pk_bf16_f32 v87, v87, v87
	s_waitcnt vmcnt(10)
	v_lshlrev_b32_e32 v88, 16, v88
	v_lshlrev_b32_e32 v89, 16, v89
	v_mul_f32_e32 v162, 0xbfb8aa3b, v88
	v_mul_f32_e32 v163, 0xbfb8aa3b, v89
	v_exp_f32_e32 v162, v162
	v_exp_f32_e32 v163, v163
	v_mul_f32_e32 v164, v39, v151
	v_mul_f32_e32 v165, v55, v151
	v_add_f32_e32 v162, 1.0, v162
	v_add_f32_e32 v163, 1.0, v163
	v_rcp_f32_e32 v162, v162
	v_rcp_f32_e32 v163, v163
	s_nop 0
	v_mul_f32_e32 v88, v162, v88
	v_mul_f32_e32 v89, v163, v89
	v_mul_f32_e32 v88, v164, v88
	v_mul_f32_e32 v89, v165, v89
	v_cvt_pk_bf16_f32 v88, v88, v88
	v_cvt_pk_bf16_f32 v89, v89, v89
	s_waitcnt vmcnt(8)
	v_lshlrev_b32_e32 v90, 16, v90
	v_lshlrev_b32_e32 v91, 16, v91
	v_mul_f32_e32 v162, 0xbfb8aa3b, v90
	v_mul_f32_e32 v163, 0xbfb8aa3b, v91
	v_exp_f32_e32 v162, v162
	v_exp_f32_e32 v163, v163
	v_mul_f32_e32 v164, v8, v152
	v_mul_f32_e32 v165, v24, v152
	v_add_f32_e32 v162, 1.0, v162
	v_add_f32_e32 v163, 1.0, v163
	v_rcp_f32_e32 v162, v162
	v_rcp_f32_e32 v163, v163
	s_nop 0
	v_mul_f32_e32 v90, v162, v90
	v_mul_f32_e32 v91, v163, v91
	v_mul_f32_e32 v90, v164, v90
	v_mul_f32_e32 v91, v165, v91
	v_cvt_pk_bf16_f32 v90, v90, v90
	v_cvt_pk_bf16_f32 v91, v91, v91
	s_waitcnt vmcnt(6)
	v_lshlrev_b32_e32 v92, 16, v92
	v_lshlrev_b32_e32 v93, 16, v93
	v_mul_f32_e32 v162, 0xbfb8aa3b, v92
	v_mul_f32_e32 v163, 0xbfb8aa3b, v93
	v_exp_f32_e32 v162, v162
	v_exp_f32_e32 v163, v163
	v_mul_f32_e32 v164, v40, v152
	v_mul_f32_e32 v165, v56, v152
	v_add_f32_e32 v162, 1.0, v162
	v_add_f32_e32 v163, 1.0, v163
	v_rcp_f32_e32 v162, v162
	v_rcp_f32_e32 v163, v163
	s_nop 0
	v_mul_f32_e32 v92, v162, v92
	v_mul_f32_e32 v93, v163, v93
	v_mul_f32_e32 v92, v164, v92
	v_mul_f32_e32 v93, v165, v93
	v_cvt_pk_bf16_f32 v92, v92, v92
	v_cvt_pk_bf16_f32 v93, v93, v93
	s_waitcnt vmcnt(4)
	v_lshlrev_b32_e32 v94, 16, v94
	v_lshlrev_b32_e32 v95, 16, v95
	v_mul_f32_e32 v162, 0xbfb8aa3b, v94
	v_mul_f32_e32 v163, 0xbfb8aa3b, v95
	v_exp_f32_e32 v162, v162
	v_exp_f32_e32 v163, v163
	v_mul_f32_e32 v164, v9, v153
	v_mul_f32_e32 v165, v25, v153
	v_add_f32_e32 v162, 1.0, v162
	v_add_f32_e32 v163, 1.0, v163
	v_rcp_f32_e32 v162, v162
	v_rcp_f32_e32 v163, v163
	s_nop 0
	v_mul_f32_e32 v94, v162, v94
	v_mul_f32_e32 v95, v163, v95
	v_mul_f32_e32 v94, v164, v94
	v_mul_f32_e32 v95, v165, v95
	v_cvt_pk_bf16_f32 v94, v94, v94
	v_cvt_pk_bf16_f32 v95, v95, v95
	s_waitcnt vmcnt(2)
	v_lshlrev_b32_e32 v96, 16, v96
	v_lshlrev_b32_e32 v97, 16, v97
	v_mul_f32_e32 v162, 0xbfb8aa3b, v96
	v_mul_f32_e32 v163, 0xbfb8aa3b, v97
	v_exp_f32_e32 v162, v162
	v_exp_f32_e32 v163, v163
	v_mul_f32_e32 v164, v41, v153
	v_mul_f32_e32 v165, v57, v153
	v_add_f32_e32 v162, 1.0, v162
	v_add_f32_e32 v163, 1.0, v163
	v_rcp_f32_e32 v162, v162
	v_rcp_f32_e32 v163, v163
	s_nop 0
	v_mul_f32_e32 v96, v162, v96
	v_mul_f32_e32 v97, v163, v97
	v_mul_f32_e32 v96, v164, v96
	v_mul_f32_e32 v97, v165, v97
	v_cvt_pk_bf16_f32 v96, v96, v96
	v_cvt_pk_bf16_f32 v97, v97, v97
	s_waitcnt vmcnt(0)
	v_lshlrev_b32_e32 v98, 16, v98
	v_lshlrev_b32_e32 v99, 16, v99
	v_mul_f32_e32 v162, 0xbfb8aa3b, v98
	v_mul_f32_e32 v163, 0xbfb8aa3b, v99
	v_exp_f32_e32 v162, v162
	v_exp_f32_e32 v163, v163
	v_mul_f32_e32 v164, v10, v154
	v_mul_f32_e32 v165, v26, v154
	v_add_f32_e32 v162, 1.0, v162
	v_add_f32_e32 v163, 1.0, v163
	v_rcp_f32_e32 v162, v162
	v_rcp_f32_e32 v163, v163
	s_nop 0
	v_mul_f32_e32 v98, v162, v98
	v_mul_f32_e32 v99, v163, v99
	v_mul_f32_e32 v98, v164, v98
	v_mul_f32_e32 v99, v165, v99
	v_cvt_pk_bf16_f32 v98, v98, v98
	v_cvt_pk_bf16_f32 v99, v99, v99
	s_mov_b32 s12, s8
	s_mov_b32 s13, s9
	global_store_short v189, v66, s[12:13] offset:0
	global_store_short v189, v67, s[12:13] offset:64
	global_store_short v189, v68, s[12:13] offset:128
	global_store_short v189, v69, s[12:13] offset:192
	s_add_u32 s12, s12, 0x1000
	s_addc_u32 s13, s13, 0
	global_store_short v189, v70, s[12:13] offset:0
	global_store_short v189, v71, s[12:13] offset:64
	global_store_short v189, v72, s[12:13] offset:128
	global_store_short v189, v73, s[12:13] offset:192
	s_add_u32 s12, s12, 0x1000
	s_addc_u32 s13, s13, 0
	global_store_short v189, v74, s[12:13] offset:0
	global_store_short v189, v75, s[12:13] offset:64
	global_store_short v189, v76, s[12:13] offset:128
	global_store_short v189, v77, s[12:13] offset:192
	s_add_u32 s12, s12, 0x1000
	s_addc_u32 s13, s13, 0
	global_store_short v189, v78, s[12:13] offset:0
	global_store_short v189, v79, s[12:13] offset:64
	global_store_short v189, v80, s[12:13] offset:128
	global_store_short v189, v81, s[12:13] offset:192
	s_add_u32 s12, s12, 0x5000
	s_addc_u32 s13, s13, 0
	global_store_short v189, v82, s[12:13] offset:0
	global_store_short v189, v83, s[12:13] offset:64
	global_store_short v189, v84, s[12:13] offset:128
	global_store_short v189, v85, s[12:13] offset:192
	s_add_u32 s12, s12, 0x1000
	s_addc_u32 s13, s13, 0
	global_store_short v189, v86, s[12:13] offset:0
	global_store_short v189, v87, s[12:13] offset:64
	global_store_short v189, v88, s[12:13] offset:128
	global_store_short v189, v89, s[12:13] offset:192
	s_add_u32 s12, s12, 0x1000
	s_addc_u32 s13, s13, 0
	global_store_short v189, v90, s[12:13] offset:0
	global_store_short v189, v91, s[12:13] offset:64
	global_store_short v189, v92, s[12:13] offset:128
	global_store_short v189, v93, s[12:13] offset:192
	s_add_u32 s12, s12, 0x1000
	s_addc_u32 s13, s13, 0
	global_store_short v189, v94, s[12:13] offset:0
	global_store_short v189, v95, s[12:13] offset:64
	global_store_short v189, v96, s[12:13] offset:128
	global_store_short v189, v97, s[12:13] offset:192
	s_add_u32 s12, s12, 0x5000
	s_addc_u32 s13, s13, 0
	global_store_short v189, v98, s[12:13] offset:0
	global_store_short v189, v99, s[12:13] offset:64
	global_store_short v189, v100, s[12:13] offset:128
	global_store_short v189, v101, s[12:13] offset:192
	s_add_u32 s12, s12, 0x1000
	s_addc_u32 s13, s13, 0
	global_store_short v189, v102, s[12:13] offset:0
	global_store_short v189, v103, s[12:13] offset:64
	global_store_short v189, v104, s[12:13] offset:128
	global_store_short v189, v105, s[12:13] offset:192
	s_add_u32 s12, s12, 0x1000
	s_addc_u32 s13, s13, 0
	global_store_short v189, v106, s[12:13] offset:0
	global_store_short v189, v107, s[12:13] offset:64
	global_store_short v189, v108, s[12:13] offset:128
	global_store_short v189, v109, s[12:13] offset:192
	s_add_u32 s12, s12, 0x1000
	s_addc_u32 s13, s13, 0
	global_store_short v189, v110, s[12:13] offset:0
	global_store_short v189, v111, s[12:13] offset:64
	global_store_short v189, v112, s[12:13] offset:128
	global_store_short v189, v113, s[12:13] offset:192
	s_add_u32 s12, s12, 0x5000
	s_addc_u32 s13, s13, 0
	global_store_short v189, v114, s[12:13] offset:0
	global_store_short v189, v115, s[12:13] offset:64
	global_store_short v189, v116, s[12:13] offset:128
	global_store_short v189, v117, s[12:13] offset:192
	s_add_u32 s12, s12, 0x1000
	s_addc_u32 s13, s13, 0
	global_store_short v189, v118, s[12:13] offset:0
	global_store_short v189, v119, s[12:13] offset:64
	global_store_short v189, v120, s[12:13] offset:128
	global_store_short v189, v121, s[12:13] offset:192
	s_add_u32 s12, s12, 0x1000
	s_addc_u32 s13, s13, 0
	global_store_short v189, v122, s[12:13] offset:0
	global_store_short v189, v123, s[12:13] offset:64
	global_store_short v189, v124, s[12:13] offset:128
	global_store_short v189, v125, s[12:13] offset:192
	s_add_u32 s12, s12, 0x1000
	s_addc_u32 s13, s13, 0
	global_store_short v189, v126, s[12:13] offset:0
	global_store_short v189, v127, s[12:13] offset:64
	global_store_short v189, v128, s[12:13] offset:128
	global_store_short v189, v129, s[12:13] offset:192
	s_branch .LBB0_109
	s_nop 0
	s_nop 0
	s_nop 0
	s_nop 0
	s_nop 0
	s_nop 0
	s_nop 0
	s_nop 0
	s_nop 0
	s_nop 0
	s_nop 0
	s_nop 0
	s_nop 0
	s_nop 0
	s_nop 0
	s_nop 0
	s_nop 0
	s_nop 0
	s_nop 0
	s_nop 0
	s_nop 0
	s_nop 0
	s_nop 0
	s_nop 0
	s_nop 0
	s_nop 0
	s_nop 0
	s_nop 0
	s_nop 0
	s_nop 0
	s_nop 0
	s_nop 0
	s_nop 0
	s_nop 0
	s_nop 0
	s_nop 0
	s_nop 0
	s_nop 0
	s_nop 0
	s_nop 0
	s_nop 0
	s_nop 0
	s_nop 0
	s_nop 0
	s_nop 0
	s_nop 0
	s_nop 0
	s_nop 0
